# GEMM K-loop heads aligned to 64 bytes (p2align 6) on top of v51
# baseline (speedup 1.0000x reference)
.LBB0_250:
	s_ashr_i32 s29, s28, 31
	s_lshl_b64 s[30:31], s[28:29], 19
	s_add_u32 s30, s56, s30
	s_addc_u32 s31, s57, s31
	s_and_b64 s[34:35], s[6:7], exec
	s_cselect_b32 s29, s31, s41
	s_cselect_b32 s73, s30, s40
	s_ashr_i32 s23, s22, 31
	s_lshl_b64 s[34:35], s[22:23], 19
	s_add_u32 s34, s58, s34
	s_addc_u32 s35, s59, s35
	s_and_b64 s[42:43], s[6:7], exec
	s_cselect_b32 s23, s35, s39
	s_cselect_b32 s74, s34, s38
	s_add_u32 s75, s38, 0x100
	s_addc_u32 s76, s39, 0
	s_add_u32 s38, s40, 0x40080
	v_mov_b32_e32 v26, 0
	s_addc_u32 s39, s41, 0
	s_mov_b32 s77, -2
	v_mov_b32_e32 v27, v26
	v_mov_b32_e32 v28, v26
	v_mov_b32_e32 v29, v26
	v_mov_b32_e32 v38, v26
	v_mov_b32_e32 v39, v26
	v_mov_b32_e32 v40, v26
	v_mov_b32_e32 v41, v26
	v_mov_b32_e32 v50, v26
	v_mov_b32_e32 v51, v26
	v_mov_b32_e32 v52, v26
	v_mov_b32_e32 v53, v26
	v_mov_b32_e32 v58, v26
	v_mov_b32_e32 v59, v26
	v_mov_b32_e32 v60, v26
	v_mov_b32_e32 v61, v26
	v_mov_b32_e32 v2, v26
	v_mov_b32_e32 v3, v26
	v_mov_b32_e32 v4, v26
	v_mov_b32_e32 v5, v26
	v_mov_b32_e32 v6, v26
	v_mov_b32_e32 v7, v26
	v_mov_b32_e32 v8, v26
	v_mov_b32_e32 v9, v26
	v_mov_b32_e32 v10, v26
	v_mov_b32_e32 v11, v26
	v_mov_b32_e32 v12, v26
	v_mov_b32_e32 v13, v26
	v_mov_b32_e32 v18, v26
	v_mov_b32_e32 v19, v26
	v_mov_b32_e32 v20, v26
	v_mov_b32_e32 v21, v26
	v_mov_b32_e32 v34, v26
	v_mov_b32_e32 v35, v26
	v_mov_b32_e32 v36, v26
	v_mov_b32_e32 v37, v26
	v_mov_b32_e32 v46, v26
	v_mov_b32_e32 v47, v26
	v_mov_b32_e32 v48, v26
	v_mov_b32_e32 v49, v26
	v_mov_b32_e32 v54, v26
	v_mov_b32_e32 v55, v26
	v_mov_b32_e32 v56, v26
	v_mov_b32_e32 v57, v26
	v_mov_b32_e32 v62, v26
	v_mov_b32_e32 v63, v26
	v_mov_b32_e32 v64, v26
	v_mov_b32_e32 v65, v26
	v_mov_b32_e32 v66, v26
	v_mov_b32_e32 v67, v26
	v_mov_b32_e32 v68, v26
	v_mov_b32_e32 v69, v26
	v_mov_b32_e32 v74, v26
	v_mov_b32_e32 v75, v26
	v_mov_b32_e32 v76, v26
	v_mov_b32_e32 v77, v26
	v_mov_b32_e32 v82, v26
	v_mov_b32_e32 v83, v26
	v_mov_b32_e32 v84, v26
	v_mov_b32_e32 v85, v26
	v_mov_b32_e32 v90, v26
	v_mov_b32_e32 v91, v26
	v_mov_b32_e32 v92, v26
	v_mov_b32_e32 v93, v26
	v_mov_b32_e32 v98, v26
	v_mov_b32_e32 v99, v26
	v_mov_b32_e32 v100, v26
	v_mov_b32_e32 v101, v26
	v_mov_b32_e32 v106, v26
	v_mov_b32_e32 v107, v26
	v_mov_b32_e32 v108, v26
	v_mov_b32_e32 v109, v26
	v_mov_b32_e32 v114, v26
	v_mov_b32_e32 v115, v26
	v_mov_b32_e32 v116, v26
	v_mov_b32_e32 v117, v26
	v_mov_b32_e32 v122, v26
	v_mov_b32_e32 v123, v26
	v_mov_b32_e32 v124, v26
	v_mov_b32_e32 v125, v26
	v_mov_b32_e32 v70, v26
	v_mov_b32_e32 v71, v26
	v_mov_b32_e32 v72, v26
	v_mov_b32_e32 v73, v26
	v_mov_b32_e32 v78, v26
	v_mov_b32_e32 v79, v26
	v_mov_b32_e32 v80, v26
	v_mov_b32_e32 v81, v26
	v_mov_b32_e32 v86, v26
	v_mov_b32_e32 v87, v26
	v_mov_b32_e32 v88, v26
	v_mov_b32_e32 v89, v26
	v_mov_b32_e32 v94, v26
	v_mov_b32_e32 v95, v26
	v_mov_b32_e32 v96, v26
	v_mov_b32_e32 v97, v26
	v_mov_b32_e32 v102, v26
	v_mov_b32_e32 v103, v26
	v_mov_b32_e32 v104, v26
	v_mov_b32_e32 v105, v26
	v_mov_b32_e32 v110, v26
	v_mov_b32_e32 v111, v26
	v_mov_b32_e32 v112, v26
	v_mov_b32_e32 v113, v26
	v_mov_b32_e32 v118, v26
	v_mov_b32_e32 v119, v26
	v_mov_b32_e32 v120, v26
	v_mov_b32_e32 v121, v26
	v_mov_b32_e32 v126, v26
	v_mov_b32_e32 v127, v26
	v_mov_b32_e32 v128, v26
	v_mov_b32_e32 v129, v26
	v_mov_b32_e32 v42, v26
	v_mov_b32_e32 v43, v26
	v_mov_b32_e32 v44, v26
	v_mov_b32_e32 v45, v26
	v_mov_b32_e32 v30, v26
	v_mov_b32_e32 v31, v26
	v_mov_b32_e32 v32, v26
	v_mov_b32_e32 v33, v26
	v_mov_b32_e32 v22, v26
	v_mov_b32_e32 v23, v26
	v_mov_b32_e32 v24, v26
	v_mov_b32_e32 v25, v26
	v_mov_b32_e32 v14, v26
	v_mov_b32_e32 v15, v26
	v_mov_b32_e32 v16, v26
	v_mov_b32_e32 v17, v26
	.p2align 6

.LBB0_472:
	s_add_u32 s95, s16, 0x100
	s_addc_u32 s96, s17, 0
	s_ashr_i32 s19, s18, 31
	s_ashr_i32 s29, s28, 31
	s_lshl_b64 s[16:17], s[28:29], 10
	s_lshl_b64 s[42:43], s[18:19], 20
	s_add_u32 s16, s30, s16
	s_addc_u32 s17, s31, s17
	s_add_u32 s42, s16, s42
	s_addc_u32 s43, s17, s43
	s_add_u32 s58, s42, 0x100
	s_addc_u32 s59, s43, 0
	v_lshl_add_u64 v[216:217], s[34:35], 0, v[208:209]
	v_lshl_add_u64 v[218:219], s[34:35], 0, v[210:211]
	s_mov_b32 s19, -2
	s_mov_b64 s[60:61], 0
	s_branch .LBB0_474
	.p2align 6

.LBB0_491:
	s_andn2_b64 vcc, exec, s[62:63]
	s_cbranch_vccnz .LBB0_493
	s_mov_b32 m0, s84
	s_nop 0
	global_load_lds_dwordx4 v[234:235], off
	s_mov_b32 m0, s85
	s_nop 0
	global_load_lds_dwordx4 v[220:221], off
	.p2align 6

.LBB0_693:
	s_ashr_i32 s41, s40, 31
	s_lshl_b64 s[42:43], s[40:41], 19
	s_add_u32 s42, s51, s42
	s_addc_u32 s43, s56, s43
	s_and_b64 s[58:59], s[10:11], exec
	s_cselect_b32 s41, s43, s65
	s_cselect_b32 s61, s42, s64
	s_ashr_i32 s39, s38, 31
	s_lshl_b64 s[58:59], s[38:39], 19
	s_add_u32 s58, s57, s58
	s_addc_u32 s59, s68, s59
	s_and_b64 s[66:67], s[10:11], exec
	s_cselect_b32 s39, s59, s63
	s_cselect_b32 s88, s58, s62
	s_add_u32 s89, s62, 0x100
	s_addc_u32 s90, s63, 0
	s_add_u32 s62, s64, 0x40080
	v_mov_b32_e32 v66, 0
	s_addc_u32 s63, s65, 0
	s_mov_b32 s91, -2
	v_mov_b32_e32 v67, v66
	v_mov_b32_e32 v68, v66
	v_mov_b32_e32 v69, v66
	v_mov_b32_e32 v70, v66
	v_mov_b32_e32 v71, v66
	v_mov_b32_e32 v72, v66
	v_mov_b32_e32 v73, v66
	v_mov_b32_e32 v90, v66
	v_mov_b32_e32 v91, v66
	v_mov_b32_e32 v92, v66
	v_mov_b32_e32 v93, v66
	v_mov_b32_e32 v94, v66
	v_mov_b32_e32 v95, v66
	v_mov_b32_e32 v96, v66
	v_mov_b32_e32 v97, v66
	v_mov_b32_e32 v2, v66
	v_mov_b32_e32 v3, v66
	v_mov_b32_e32 v4, v66
	v_mov_b32_e32 v5, v66
	v_mov_b32_e32 v6, v66
	v_mov_b32_e32 v7, v66
	v_mov_b32_e32 v8, v66
	v_mov_b32_e32 v9, v66
	v_mov_b32_e32 v10, v66
	v_mov_b32_e32 v11, v66
	v_mov_b32_e32 v12, v66
	v_mov_b32_e32 v13, v66
	v_mov_b32_e32 v14, v66
	v_mov_b32_e32 v15, v66
	v_mov_b32_e32 v16, v66
	v_mov_b32_e32 v17, v66
	v_mov_b32_e32 v18, v66
	v_mov_b32_e32 v19, v66
	v_mov_b32_e32 v20, v66
	v_mov_b32_e32 v21, v66
	v_mov_b32_e32 v22, v66
	v_mov_b32_e32 v23, v66
	v_mov_b32_e32 v24, v66
	v_mov_b32_e32 v25, v66
	v_mov_b32_e32 v26, v66
	v_mov_b32_e32 v27, v66
	v_mov_b32_e32 v28, v66
	v_mov_b32_e32 v29, v66
	v_mov_b32_e32 v30, v66
	v_mov_b32_e32 v31, v66
	v_mov_b32_e32 v32, v66
	v_mov_b32_e32 v33, v66
	v_mov_b32_e32 v98, v66
	v_mov_b32_e32 v99, v66
	v_mov_b32_e32 v100, v66
	v_mov_b32_e32 v101, v66
	v_mov_b32_e32 v102, v66
	v_mov_b32_e32 v103, v66
	v_mov_b32_e32 v104, v66
	v_mov_b32_e32 v105, v66
	v_mov_b32_e32 v106, v66
	v_mov_b32_e32 v107, v66
	v_mov_b32_e32 v108, v66
	v_mov_b32_e32 v109, v66
	v_mov_b32_e32 v110, v66
	v_mov_b32_e32 v111, v66
	v_mov_b32_e32 v112, v66
	v_mov_b32_e32 v113, v66
	v_mov_b32_e32 v114, v66
	v_mov_b32_e32 v115, v66
	v_mov_b32_e32 v116, v66
	v_mov_b32_e32 v117, v66
	v_mov_b32_e32 v118, v66
	v_mov_b32_e32 v119, v66
	v_mov_b32_e32 v120, v66
	v_mov_b32_e32 v121, v66
	v_mov_b32_e32 v122, v66
	v_mov_b32_e32 v123, v66
	v_mov_b32_e32 v124, v66
	v_mov_b32_e32 v125, v66
	v_mov_b32_e32 v126, v66
	v_mov_b32_e32 v127, v66
	v_mov_b32_e32 v128, v66
	v_mov_b32_e32 v129, v66
	v_mov_b32_e32 v34, v66
	v_mov_b32_e32 v35, v66
	v_mov_b32_e32 v36, v66
	v_mov_b32_e32 v37, v66
	v_mov_b32_e32 v38, v66
	v_mov_b32_e32 v39, v66
	v_mov_b32_e32 v40, v66
	v_mov_b32_e32 v41, v66
	v_mov_b32_e32 v42, v66
	v_mov_b32_e32 v43, v66
	v_mov_b32_e32 v44, v66
	v_mov_b32_e32 v45, v66
	v_mov_b32_e32 v46, v66
	v_mov_b32_e32 v47, v66
	v_mov_b32_e32 v48, v66
	v_mov_b32_e32 v49, v66
	v_mov_b32_e32 v50, v66
	v_mov_b32_e32 v51, v66
	v_mov_b32_e32 v52, v66
	v_mov_b32_e32 v53, v66
	v_mov_b32_e32 v54, v66
	v_mov_b32_e32 v55, v66
	v_mov_b32_e32 v56, v66
	v_mov_b32_e32 v57, v66
	v_mov_b32_e32 v58, v66
	v_mov_b32_e32 v59, v66
	v_mov_b32_e32 v60, v66
	v_mov_b32_e32 v61, v66
	v_mov_b32_e32 v62, v66
	v_mov_b32_e32 v63, v66
	v_mov_b32_e32 v64, v66
	v_mov_b32_e32 v65, v66
	v_mov_b32_e32 v82, v66
	v_mov_b32_e32 v83, v66
	v_mov_b32_e32 v84, v66
	v_mov_b32_e32 v85, v66
	v_mov_b32_e32 v86, v66
	v_mov_b32_e32 v87, v66
	v_mov_b32_e32 v88, v66
	v_mov_b32_e32 v89, v66
	v_mov_b32_e32 v74, v66
	v_mov_b32_e32 v75, v66
	v_mov_b32_e32 v76, v66
	v_mov_b32_e32 v77, v66
	v_mov_b32_e32 v78, v66
	v_mov_b32_e32 v79, v66
	v_mov_b32_e32 v80, v66
	v_mov_b32_e32 v81, v66
	.p2align 6

.LBB0_1770:
	s_add_u32 s51, s12, 0x100
	s_addc_u32 s84, s13, 0
	s_ashr_i32 s29, s28, 31
	s_lshl_b64 s[30:31], s[28:29], 19
	s_add_u32 s34, s63, s30
	s_addc_u32 s35, s64, s31
	s_and_b64 s[30:31], s[10:11], exec
	s_cselect_b32 s29, s35, s23
	s_cselect_b32 s85, s34, s22
	s_ashr_i32 s27, s26, 31
	s_lshl_b64 s[30:31], s[26:27], 19
	s_add_u32 s30, s65, s30
	s_addc_u32 s31, s66, s31
	s_and_b64 s[36:37], s[10:11], exec
	s_cselect_b32 s27, s31, s13
	s_cselect_b32 s86, s30, s12
	s_ashr_i32 s15, s14, 31
	s_ashr_i32 s21, s20, 31
	s_lshl_b64 s[12:13], s[20:21], 9
	s_lshl_b64 s[36:37], s[14:15], 19
	s_add_u32 s12, s16, s12
	s_addc_u32 s13, s17, s13
	s_add_u32 s36, s12, s36
	s_addc_u32 s37, s13, s37
	s_add_u32 s38, s36, 0x100
	s_addc_u32 s39, s37, 0
	v_lshl_add_u64 v[216:217], s[22:23], 0, v[208:209]
	v_lshl_add_u64 v[218:219], s[22:23], 0, v[210:211]
	s_mov_b32 s15, -2
	s_mov_b64 s[40:41], 0
	s_branch .LBB0_1772
	.p2align 6

.LBB0_1974:
	s_ashr_i32 s27, s26, 31
	s_lshl_b64 s[28:29], s[26:27], 19
	s_add_u32 s28, s42, s28
	s_addc_u32 s29, s43, s29
	s_and_b64 s[30:31], s[10:11], exec
	s_cselect_b32 s27, s29, s39
	s_cselect_b32 s65, s28, s38
	s_ashr_i32 s25, s24, 31
	s_lshl_b64 s[30:31], s[24:25], 19
	s_add_u32 s30, s54, s30
	s_addc_u32 s31, s55, s31
	s_and_b64 s[40:41], s[10:11], exec
	s_cselect_b32 s25, s31, s37
	s_cselect_b32 s66, s30, s36
	s_add_u32 s67, s36, 0x100
	s_addc_u32 s68, s37, 0
	s_add_u32 s36, s38, 0x40080
	v_mov_b32_e32 v26, 0
	s_addc_u32 s37, s39, 0
	s_mov_b32 s69, -2
	v_mov_b32_e32 v27, v26
	v_mov_b32_e32 v28, v26
	v_mov_b32_e32 v29, v26
	v_mov_b32_e32 v38, v26
	v_mov_b32_e32 v39, v26
	v_mov_b32_e32 v40, v26
	v_mov_b32_e32 v41, v26
	v_mov_b32_e32 v50, v26
	v_mov_b32_e32 v51, v26
	v_mov_b32_e32 v52, v26
	v_mov_b32_e32 v53, v26
	v_mov_b32_e32 v58, v26
	v_mov_b32_e32 v59, v26
	v_mov_b32_e32 v60, v26
	v_mov_b32_e32 v61, v26
	v_mov_b32_e32 v2, v26
	v_mov_b32_e32 v3, v26
	v_mov_b32_e32 v4, v26
	v_mov_b32_e32 v5, v26
	v_mov_b32_e32 v6, v26
	v_mov_b32_e32 v7, v26
	v_mov_b32_e32 v8, v26
	v_mov_b32_e32 v9, v26
	v_mov_b32_e32 v10, v26
	v_mov_b32_e32 v11, v26
	v_mov_b32_e32 v12, v26
	v_mov_b32_e32 v13, v26
	v_mov_b32_e32 v18, v26
	v_mov_b32_e32 v19, v26
	v_mov_b32_e32 v20, v26
	v_mov_b32_e32 v21, v26
	v_mov_b32_e32 v34, v26
	v_mov_b32_e32 v35, v26
	v_mov_b32_e32 v36, v26
	v_mov_b32_e32 v37, v26
	v_mov_b32_e32 v46, v26
	v_mov_b32_e32 v47, v26
	v_mov_b32_e32 v48, v26
	v_mov_b32_e32 v49, v26
	v_mov_b32_e32 v54, v26
	v_mov_b32_e32 v55, v26
	v_mov_b32_e32 v56, v26
	v_mov_b32_e32 v57, v26
	v_mov_b32_e32 v62, v26
	v_mov_b32_e32 v63, v26
	v_mov_b32_e32 v64, v26
	v_mov_b32_e32 v65, v26
	v_mov_b32_e32 v66, v26
	v_mov_b32_e32 v67, v26
	v_mov_b32_e32 v68, v26
	v_mov_b32_e32 v69, v26
	v_mov_b32_e32 v74, v26
	v_mov_b32_e32 v75, v26
	v_mov_b32_e32 v76, v26
	v_mov_b32_e32 v77, v26
	v_mov_b32_e32 v82, v26
	v_mov_b32_e32 v83, v26
	v_mov_b32_e32 v84, v26
	v_mov_b32_e32 v85, v26
	v_mov_b32_e32 v90, v26
	v_mov_b32_e32 v91, v26
	v_mov_b32_e32 v92, v26
	v_mov_b32_e32 v93, v26
	v_mov_b32_e32 v98, v26
	v_mov_b32_e32 v99, v26
	v_mov_b32_e32 v100, v26
	v_mov_b32_e32 v101, v26
	v_mov_b32_e32 v106, v26
	v_mov_b32_e32 v107, v26
	v_mov_b32_e32 v108, v26
	v_mov_b32_e32 v109, v26
	v_mov_b32_e32 v114, v26
	v_mov_b32_e32 v115, v26
	v_mov_b32_e32 v116, v26
	v_mov_b32_e32 v117, v26
	v_mov_b32_e32 v122, v26
	v_mov_b32_e32 v123, v26
	v_mov_b32_e32 v124, v26
	v_mov_b32_e32 v125, v26
	v_mov_b32_e32 v70, v26
	v_mov_b32_e32 v71, v26
	v_mov_b32_e32 v72, v26
	v_mov_b32_e32 v73, v26
	v_mov_b32_e32 v78, v26
	v_mov_b32_e32 v79, v26
	v_mov_b32_e32 v80, v26
	v_mov_b32_e32 v81, v26
	v_mov_b32_e32 v86, v26
	v_mov_b32_e32 v87, v26
	v_mov_b32_e32 v88, v26
	v_mov_b32_e32 v89, v26
	v_mov_b32_e32 v94, v26
	v_mov_b32_e32 v95, v26
	v_mov_b32_e32 v96, v26
	v_mov_b32_e32 v97, v26
	v_mov_b32_e32 v102, v26
	v_mov_b32_e32 v103, v26
	v_mov_b32_e32 v104, v26
	v_mov_b32_e32 v105, v26
	v_mov_b32_e32 v110, v26
	v_mov_b32_e32 v111, v26
	v_mov_b32_e32 v112, v26
	v_mov_b32_e32 v113, v26
	v_mov_b32_e32 v118, v26
	v_mov_b32_e32 v119, v26
	v_mov_b32_e32 v120, v26
	v_mov_b32_e32 v121, v26
	v_mov_b32_e32 v126, v26
	v_mov_b32_e32 v127, v26
	v_mov_b32_e32 v128, v26
	v_mov_b32_e32 v129, v26
	v_mov_b32_e32 v42, v26
	v_mov_b32_e32 v43, v26
	v_mov_b32_e32 v44, v26
	v_mov_b32_e32 v45, v26
	v_mov_b32_e32 v30, v26
	v_mov_b32_e32 v31, v26
	v_mov_b32_e32 v32, v26
	v_mov_b32_e32 v33, v26
	v_mov_b32_e32 v22, v26
	v_mov_b32_e32 v23, v26
	v_mov_b32_e32 v24, v26
	v_mov_b32_e32 v25, v26
	v_mov_b32_e32 v14, v26
	v_mov_b32_e32 v15, v26
	v_mov_b32_e32 v16, v26
	v_mov_b32_e32 v17, v26
	.p2align 6

.LBB0_2015:
	v_mov_b32_e32 v3, v0
	s_and_b32 s8, s2, 7
	v_ashrrev_i32_e32 v2, 31, v3
	v_lshrrev_b32_e32 v2, 26, v2
	v_add_u32_e32 v16, v3, v2
	v_bfe_i32 v2, v3, 27, 1
	v_lshlrev_b32_e32 v5, 4, v3
	v_lshrrev_b32_e32 v2, 22, v2
	v_add_u32_e32 v2, v5, v2
	v_and_b32_e32 v2, 0xfffffc00, v2
	v_sub_u32_e32 v2, v5, v2
	v_lshrrev_b32_e32 v4, 4, v2
	v_bitop3_b32 v2, v4, v2, 32 bitop3:0x6c
	v_ashrrev_i32_e32 v6, 31, v2
	v_lshrrev_b32_e32 v6, 26, v6
	v_ashrrev_i32_e32 v17, 6, v16
	v_add_u32_e32 v6, v2, v6
	v_lshlrev_b32_e32 v4, 3, v17
	v_ashrrev_i32_e32 v18, 6, v6
	v_and_b32_e32 v6, 0xc0, v6
	v_and_b32_e32 v4, -16, v4
	v_sub_u32_e32 v2, v2, v6
	v_mov_b32_e32 v6, 1
	v_add_u32_e32 v4, v18, v4
	v_ashrrev_i16_sdwa v2, v6, sext(v2) dst_sel:DWORD dst_unused:UNUSED_PAD src0_sel:DWORD src1_sel:BYTE_0
	v_bfe_i32 v19, v2, 0, 16
	v_lshlrev_b32_e32 v2, 1, v4
	v_lshlrev_b32_e32 v7, 5, v17
	v_and_b32_e32 v20, 0x1fffe0, v4
	v_and_b32_e32 v21, 24, v2
	v_lshrrev_b32_e32 v2, 2, v4
	v_and_b32_e32 v23, 3, v18
	v_and_b32_e32 v7, 32, v7
	v_and_b32_e32 v22, 4, v2
	v_or_b32_e32 v2, v20, v23
	v_or3_b32 v2, v2, v22, v21
	v_add_lshl_u32 v7, v7, v19, 1
	v_add_u32_e32 v5, 0x2000, v5
	v_lshl_add_u32 v4, v4, 11, v7
	v_lshl_add_u32 v2, v2, 11, v7
	v_ashrrev_i32_e32 v7, 31, v5
	v_lshrrev_b32_e32 v7, 22, v7
	v_add_u32_e32 v7, v5, v7
	v_ashrrev_i32_e32 v24, 10, v7
	s_mulk_i32 s8, 0xb0
	s_bfe_u32 s9, s2, 0x40003
	v_mul_i32_i24_e32 v7, 0x400, v24
	s_or_b32 s8, s8, s9
	v_sub_u32_e32 v5, v5, v7
	s_add_i32 s25, s8, 0xa0
	v_lshrrev_b32_e32 v7, 4, v5
	s_mul_i32 s8, s25, 0xba2f
	v_bitop3_b32 v5, v7, v5, 32 bitop3:0x6c
	s_lshr_b32 s8, s8, 22
	v_ashrrev_i32_e32 v8, 31, v5
	s_mul_i32 s9, s8, 0x58
	v_lshrrev_b32_e32 v8, 26, v8
	s_sub_i32 s9, s25, s9
	v_add_u32_e32 v8, v5, v8
	s_lshl_b32 s8, s8, 2
	s_and_b32 s26, s9, 3
	v_lshlrev_b32_e32 v7, 3, v24
	v_ashrrev_i32_e32 v25, 6, v8
	v_and_b32_e32 v8, 0xc0, v8
	s_or_b32 s20, s26, s8
	v_readfirstlane_b32 s8, v3
	v_and_b32_e32 v7, -16, v7
	v_sub_u32_e32 v5, v5, v8
	s_ashr_i32 s16, s8, 6
	v_add_u32_e32 v7, v25, v7
	v_ashrrev_i16_sdwa v5, v6, sext(v5) dst_sel:DWORD dst_unused:UNUSED_PAD src0_sel:DWORD src1_sel:BYTE_0
	s_ashr_i32 s8, s8, 2
	s_bfe_u32 s19, s9, 0xe0002
	s_ashr_i32 s18, s2, 7
	v_bfe_i32 v26, v5, 0, 16
	v_lshlrev_b32_e32 v5, 1, v7
	s_and_b32 s17, s8, 0xffffffc0
	s_lshl_b32 s21, s16, 5
	s_lshl_b32 s24, s20, 19
	v_lshlrev_b32_e32 v9, 5, v24
	v_and_b32_e32 v27, 0x1fffe0, v7
	v_and_b32_e32 v28, 24, v5
	v_lshrrev_b32_e32 v5, 2, v7
	v_and_b32_e32 v30, 3, v25
	s_cmp_gt_i32 s18, 0
	v_and_b32_e32 v9, 32, v9
	v_and_b32_e32 v29, 4, v5
	v_or_b32_e32 v5, v27, v30
	s_cselect_b64 s[8:9], -1, 0
	v_or3_b32 v5, v5, v29, v28
	v_add_lshl_u32 v8, v9, v26, 1
	s_and_b64 s[10:11], s[8:9], exec
	v_lshl_add_u32 v6, v7, 11, v8
	v_lshl_add_u32 v8, v5, 11, v8
	v_and_b32_e32 v5, 15, v3
	s_cselect_b32 s27, 0x40000, 0
	s_and_b32 s21, s21, 0x60
	v_or_b32_e32 v74, s17, v5
	s_lshl_b32 s28, s19, 19
	s_lshl_b32 s16, s16, 10
	s_lshl_b32 s23, s17, 7
	s_lshl_b32 s17, s21, 7
	s_add_u32 s29, s42, s24
	s_addc_u32 s30, s43, 0
	s_add_u32 s10, s54, s28
	v_lshrrev_b32_e32 v7, 1, v3
	s_addc_u32 s11, s55, 0
	s_add_i32 s24, s16, 0
	v_and_b32_e32 v75, 24, v7
	s_mov_b32 m0, s24
	v_lshlrev_b32_e32 v31, 1, v75
	v_lshlrev_b32_e32 v32, 6, v5
	v_lshlrev_b32_e32 v3, 2, v3
	global_load_lds_dwordx4 v2, s[10:11]
	s_add_i32 m0, s24, 0x2000
	v_or_b32_e32 v5, v32, v31
	v_and_b32_e32 v33, 32, v3
	s_add_u32 s16, s10, 0x40000
	global_load_lds_dwordx4 v8, s[10:11]
	v_bitop3_b32 v76, v5, s17, v33 bitop3:0xde
	s_addc_u32 s17, s11, 0
	s_add_i32 m0, s24, 0x4000
	v_mov_b32_e32 v3, 0
	global_load_lds_dwordx4 v2, s[16:17]
	s_add_i32 m0, s24, 0x6000
	v_mov_b32_e32 v5, v3
	global_load_lds_dwordx4 v8, s[16:17]
	s_add_u32 s16, s29, s27
	s_addc_u32 s17, s30, 0
	s_add_i32 m0, s24, 0x8000
	v_mov_b32_e32 v7, v3
	global_load_lds_dwordx4 v4, s[16:17]
	s_add_i32 m0, s24, 0xa000
	v_lshl_add_u64 v[10:11], s[10:11], 0, v[2:3]
	v_lshl_add_u64 v[14:15], s[16:17], 0, v[4:5]
	v_lshl_add_u64 v[4:5], s[16:17], 0, v[6:7]
	global_load_lds_dwordx4 v6, s[16:17]
	s_mov_b64 s[16:17], 0x80
	v_mov_b32_e32 v9, v3
	s_add_i32 m0, s24, 0xc000
	v_lshl_add_u64 v[6:7], v[10:11], 0, s[16:17]
	v_lshl_add_u64 v[12:13], s[10:11], 0, v[8:9]
	global_load_lds_dwordx4 v[6:7], off
	s_add_i32 m0, s24, 0xe000
	v_lshl_add_u64 v[6:7], v[12:13], 0, s[16:17]
	s_add_u32 s10, s10, 0x40080
	global_load_lds_dwordx4 v[6:7], off
	s_addc_u32 s11, s11, 0
	s_add_i32 m0, s24, 0x10000
	v_lshl_add_u64 v[6:7], v[14:15], 0, s[16:17]
	global_load_lds_dwordx4 v2, s[10:11]
	s_add_i32 m0, s24, 0x12000
	v_lshl_add_u64 v[4:5], v[4:5], 0, s[16:17]
	global_load_lds_dwordx4 v8, s[10:11]
	s_add_i32 m0, s24, 0x14000
	s_mul_hi_u32 s10, s25, 0x2e8ba2f
	global_load_lds_dwordx4 v[6:7], off
	s_add_i32 m0, s24, 0x16000
	s_lshl_b32 s10, s10, 21
	global_load_lds_dwordx4 v[4:5], off
	s_lshl_b32 s11, s26, 19
	v_lshlrev_b32_e32 v2, 14, v24
	s_or_b32 s10, s10, s11
	v_and_b32_e32 v2, 0xffff8000, v2
	v_lshlrev_b32_e32 v4, 6, v24
	s_add_u32 s10, s14, s10
	v_lshl_add_u32 v2, v25, 11, v2
	v_and_b32_e32 v6, 64, v4
	s_addc_u32 s11, s15, 0
	v_or_b32_e32 v2, v2, v6
	v_lshlrev_b32_e32 v7, 1, v26
	s_add_u32 s10, s10, s27
	v_add_u32_e32 v2, v2, v7
	s_addc_u32 s11, s11, 0
	v_lshl_add_u64 v[4:5], s[10:11], 0, v[2:3]
	v_lshlrev_b32_e32 v2, 14, v17
	v_and_b32_e32 v2, 0xffff8000, v2
	v_lshl_add_u32 v2, v18, 11, v2
	v_and_b32_e32 v8, 64, v16
	v_or_b32_e32 v2, v2, v8
	v_lshlrev_b32_e32 v9, 1, v19
	s_mov_b64 s[16:17], 0x3000100
	v_add_u32_e32 v2, v2, v9
	v_lshl_add_u64 v[66:67], v[4:5], 0, s[16:17]
	v_lshl_add_u64 v[4:5], s[10:11], 0, v[2:3]
	v_or_b32_e32 v2, v27, v28
	v_or3_b32 v2, v2, v29, v30
	v_lshl_or_b32 v2, v2, 11, v6
	s_add_u32 s10, s14, s28
	v_add_u32_e32 v2, v2, v7
	s_addc_u32 s11, s15, 0
	v_lshl_add_u64 v[70:71], s[10:11], 0, v[2:3]
	v_or_b32_e32 v2, v20, v21
	v_or3_b32 v2, v2, v22, v23
	v_lshl_or_b32 v2, v2, 11, v8
	v_add_u32_e32 v2, v2, v9
	s_mov_b32 s22, 0
	v_bitop3_b32 v77, v32, v33, v31 bitop3:0x36
	v_lshl_add_u64 v[68:69], v[4:5], 0, s[16:17]
	v_lshl_add_u64 v[72:73], s[10:11], 0, v[2:3]
	s_mov_b64 s[10:11], 0
	s_mov_b64 s[14:15], 0x1f00100
	s_mov_b64 s[16:17], 0x1f40100
	v_mov_b32_e32 v2, v3
	v_mov_b32_e32 v4, v3
	v_mov_b32_e32 v5, v3
	v_mov_b32_e32 v6, v3
	v_mov_b32_e32 v7, v3
	v_mov_b32_e32 v8, v3
	v_mov_b32_e32 v9, v3
	v_mov_b32_e32 v10, v3
	v_mov_b32_e32 v11, v3
	v_mov_b32_e32 v12, v3
	v_mov_b32_e32 v13, v3
	v_mov_b32_e32 v14, v3
	v_mov_b32_e32 v15, v3
	v_mov_b32_e32 v16, v3
	v_mov_b32_e32 v17, v3
	v_mov_b32_e32 v18, v3
	v_mov_b32_e32 v19, v3
	v_mov_b32_e32 v20, v3
	v_mov_b32_e32 v21, v3
	v_mov_b32_e32 v26, v3
	v_mov_b32_e32 v27, v3
	v_mov_b32_e32 v28, v3
	v_mov_b32_e32 v29, v3
	v_mov_b32_e32 v34, v3
	v_mov_b32_e32 v35, v3
	v_mov_b32_e32 v36, v3
	v_mov_b32_e32 v37, v3
	v_mov_b32_e32 v42, v3
	v_mov_b32_e32 v43, v3
	v_mov_b32_e32 v44, v3
	v_mov_b32_e32 v45, v3
	v_mov_b32_e32 v22, v3
	v_mov_b32_e32 v23, v3
	v_mov_b32_e32 v24, v3
	v_mov_b32_e32 v25, v3
	v_mov_b32_e32 v30, v3
	v_mov_b32_e32 v31, v3
	v_mov_b32_e32 v32, v3
	v_mov_b32_e32 v33, v3
	v_mov_b32_e32 v38, v3
	v_mov_b32_e32 v39, v3
	v_mov_b32_e32 v40, v3
	v_mov_b32_e32 v41, v3
	v_mov_b32_e32 v46, v3
	v_mov_b32_e32 v47, v3
	v_mov_b32_e32 v48, v3
	v_mov_b32_e32 v49, v3
	v_mov_b32_e32 v50, v3
	v_mov_b32_e32 v51, v3
	v_mov_b32_e32 v52, v3
	v_mov_b32_e32 v53, v3
	v_mov_b32_e32 v54, v3
	v_mov_b32_e32 v55, v3
	v_mov_b32_e32 v56, v3
	v_mov_b32_e32 v57, v3
	v_mov_b32_e32 v58, v3
	v_mov_b32_e32 v59, v3
	v_mov_b32_e32 v60, v3
	v_mov_b32_e32 v61, v3
	v_mov_b32_e32 v62, v3
	v_mov_b32_e32 v63, v3
	v_mov_b32_e32 v64, v3
	v_mov_b32_e32 v65, v3
	.p2align 6

.LBB0_2129:
	s_add_u32 s74, s6, 0x100
	s_addc_u32 s75, s7, 0
	s_ashr_i32 s17, s16, 31
	s_ashr_i32 s19, s18, 31
	s_lshl_b64 s[6:7], s[18:19], 9
	s_lshl_b64 s[30:31], s[16:17], 19
	s_add_u32 s6, s20, s6
	s_addc_u32 s7, s21, s7
	s_add_u32 s30, s6, s30
	s_addc_u32 s31, s7, s31
	s_add_u32 s34, s30, 0x100
	s_addc_u32 s35, s31, 0
	v_lshl_add_u64 v[216:217], s[22:23], 0, v[208:209]
	v_lshl_add_u64 v[218:219], s[22:23], 0, v[210:211]
	s_mov_b32 s17, -2
	s_mov_b64 s[36:37], 0
	s_branch .LBB0_2131
	.p2align 6
